# finalize position load joined into the hoisted per-token load batch (on top of v14)
# baseline (speedup 1.0000x reference)
; DI float bflo(unsigned w) { return __uint_as_float(w << 16); }
; DI float bfhi(unsigned w) { return __uint_as_float(w & 0xffff0000u); }
; DI void mla_finalize(PPtr p, int j, ldsp lds, int tid, int wave, int lane) {
;     ...
;             const float rq = rsqrtf(wave_sum(ssq) * (1.0f / QL) + EPS), rkv = rsqrtf(wave_sum(sskv) * (1.0f / KVL) + EPS);
;             float cs, sn;
;             { const int fi = lane & 15; const float inv = exp2f(-(float)fi * (13.287712379549449f / 16.0f));
;               const float ang = (float)p->pos[t] * inv; double rev = (double)ang * 0.15915494309189535; rev -= floor(rev); const float rv = (float)rev;
;               cs = __builtin_amdgcn_cosf(rv); sn = __builtin_amdgcn_sinf(rv); }
;             float cj[8], sj[8];
; #pragma unroll
;             for (int i = 0; i < 8; ++i) { cj[i] = __shfl(cs, 8 * (sub & 1) + i); sj[i] = __shfl(sn, 8 * (sub & 1) + i); }
; #pragma unroll
;             for (int which = 0; which < 2; ++which) {
;                 float v[24];
;                 if (which == 0) {
;                     const bf16_t* src = qraw + (size_t)t * 1536 + head * QKH;
; #pragma unroll
;                     for (int g = 0; g < 3; ++g) { const u32x4 w = *(const u32x4*)(src + 8 * (sub + 4 * g));
; #pragma unroll
;                         for (int i = 0; i < 4; ++i) { v[8 * g + 2 * i] = bflo(w[i]) * rq; v[8 * g + 2 * i + 1] = bfhi(w[i]) * rq; } }
.LBB0_786:
	s_or_b64 exec, exec, s[10:11]
	s_lshl_b64 s[10:11], s[14:15], 2
	s_add_u32 s10, s12, s10
	s_addc_u32 s11, s13, s11
	ds_bpermute_b32 v4, v39, v2
	ds_bpermute_b32 v5, v39, v3
	s_mov_b32 s10, 0x6dc9c883
	s_mov_b32 s11, 0x3fc45f30
	v_lshl_add_u64 v[106:107], v[64:65], 0, s[8:9]
	s_mov_b32 s8, 0x3b2aaaab
	s_waitcnt lgkmcnt(0)
	v_pk_add_f32 v[2:3], v[2:3], v[4:5]
	ds_bpermute_b32 v4, v77, v2
	ds_bpermute_b32 v5, v77, v3
	s_mov_b32 s9, 0x3b800000
	v_mov_b32_e32 v69, v1
	s_waitcnt lgkmcnt(0)
	v_pk_add_f32 v[2:3], v[2:3], v[4:5]
	ds_bpermute_b32 v4, v130, v2
	ds_bpermute_b32 v5, v130, v3
	s_waitcnt lgkmcnt(0)
	v_pk_add_f32 v[2:3], v[2:3], v[4:5]
	ds_bpermute_b32 v4, v131, v2
	ds_bpermute_b32 v5, v131, v3
	s_waitcnt lgkmcnt(0)
	v_pk_add_f32 v[2:3], v[2:3], v[4:5]
	ds_bpermute_b32 v4, v132, v2
	ds_bpermute_b32 v5, v132, v3
	s_waitcnt lgkmcnt(0)
	v_pk_add_f32 v[2:3], v[2:3], v[4:5]
	ds_bpermute_b32 v4, v133, v2
	ds_bpermute_b32 v5, v133, v3
	s_waitcnt lgkmcnt(0)
	v_pk_add_f32 v[2:3], v[2:3], v[4:5]
	s_nop 0
	v_pk_fma_f32 v[2:3], v[2:3], s[8:9], v[152:153] op_sel_hi:[1,1,0]
	v_mov_b32_e32 v6, v179
	v_cvt_f32_i32_e32 v6, v6
	v_mul_f32_e32 v4, 0x4b800000, v3
	v_cmp_gt_f32_e64 s[8:9], s91, v2
	v_mul_f32_e32 v6, v134, v6
	v_cvt_f64_f32_e32 v[6:7], v6
	v_mul_f64 v[8:9], v[6:7], s[10:11]
	v_floor_f64_e32 v[8:9], v[8:9]
	v_fma_f64 v[6:7], v[6:7], s[10:11], -v[8:9]
	v_cvt_f32_f64_e32 v6, v[6:7]
	v_cos_f32_e32 v7, v6
	v_sin_f32_e32 v6, v6
	s_lshl_b64 s[10:11], s[14:15], 4
	v_or_b32_e32 v8, s10, v38
	ds_bpermute_b32 v100, v135, v7
	ds_bpermute_b32 v102, v135, v6
	ds_bpermute_b32 v101, v136, v7
	ds_bpermute_b32 v105, v136, v6
	ds_bpermute_b32 v94, v137, v7
	ds_bpermute_b32 v96, v137, v6
	ds_bpermute_b32 v95, v138, v7
	ds_bpermute_b32 v99, v138, v6
	ds_bpermute_b32 v88, v139, v7
	ds_bpermute_b32 v90, v139, v6
	ds_bpermute_b32 v89, v140, v7
	ds_bpermute_b32 v93, v140, v6
	ds_bpermute_b32 v80, v141, v7
	ds_bpermute_b32 v82, v141, v6
	ds_bpermute_b32 v81, v142, v7
	ds_bpermute_b32 v87, v142, v6
	v_mov_b64_e32 v[6:7], s[2:3]
	s_movk_i32 s10, 0xc0
	v_mad_u64_u32 v[84:85], s[22:23], v8, s10, v[6:7]
	v_mov_b32_e32 v6, 0xc0
	v_mad_i32_i24 v85, s11, v6, v85
	s_lshl_b64 s[10:11], s[14:15], 12
	v_lshl_add_u64 v[78:79], v[40:41], 0, s[10:11]
	v_cmp_gt_f32_e64 s[10:11], s91, v3
	s_nop 1
	v_cndmask_b32_e64 v3, v3, v4, s[10:11]
	v_rsq_f32_e32 v3, v3
	s_nop 0
	v_mul_f32_e32 v4, 0x45800000, v3
	v_cndmask_b32_e64 v76, v3, v4, s[10:11]
	v_mul_f32_e32 v3, 0x4b800000, v2
	v_cndmask_b32_e64 v2, v2, v3, s[8:9]
	v_rsq_f32_e32 v2, v2
	s_nop 0
	v_mul_f32_e32 v3, 0x45800000, v2
	v_cndmask_b32_e64 v86, v2, v3, s[8:9]
	v_mov_b32_e32 v2, 0xc00
	v_mad_i64_i32 v[2:3], s[8:9], s14, v2, v[66:67]
	s_mov_b64 s[8:9], 0x15a40000
	v_lshl_add_u64 v[110:111], v[84:85], 0, s[8:9]
	v_lshl_add_u64 v[168:169], v[110:111], 0, v[68:69]
	s_add_i32 s14, s14, 1
	v_mov_b32_e32 v34, v192
	v_mov_b32_e32 v35, v193
	v_mov_b32_e32 v36, v194
	v_mov_b32_e32 v37, v195
	v_lshlrev_b32_e32 v118, 16, v36
	v_and_b32_e32 v119, 0xffff0000, v36
	v_mov_b32_e32 v10, v196
	v_mov_b32_e32 v11, v197
	v_mov_b32_e32 v12, v198
	v_mov_b32_e32 v13, v199
	v_mov_b32_e32 v6, v206
	v_mov_b32_e32 v7, v207
	v_mov_b32_e32 v8, v208
	v_mov_b32_e32 v9, v209
	v_and_b32_e32 v2, 0xffff0000, v8
	v_lshlrev_b32_e32 v3, 16, v8
	s_waitcnt lgkmcnt(0)
	v_pk_mul_f32 v[108:109], v[86:87], v[2:3] op_sel_hi:[0,1]
	v_and_b32_e32 v2, 0xffff0000, v9
	v_lshlrev_b32_e32 v3, 16, v9
	v_pk_mul_f32 v[8:9], v[86:87], v[2:3] op_sel_hi:[0,1]
	global_load_dwordx4 v[22:25], v[44:45], off
	global_load_dwordx4 v[26:29], v[44:45], off offset:16
	global_load_dwordx4 v[18:21], v[44:45], off offset:128
	global_load_dwordx4 v[14:17], v[44:45], off offset:144
	global_load_dwordx4 v[2:5], v[44:45], off offset:272
	global_load_dwordx4 v[30:33], v[44:45], off offset:256
	v_lshlrev_b32_e32 v120, 16, v34
	v_and_b32_e32 v121, 0xffff0000, v34
	v_lshlrev_b32_e32 v116, 16, v37
	v_and_b32_e32 v117, 0xffff0000, v37
	v_pk_mul_f32 v[36:37], v[86:87], v[118:119] op_sel_hi:[0,1]
	v_lshlrev_b32_e32 v118, 16, v35
	v_and_b32_e32 v119, 0xffff0000, v35
	v_pk_mul_f32 v[120:121], v[86:87], v[120:121] op_sel_hi:[0,1]
	v_pk_mul_f32 v[118:119], v[86:87], v[118:119] op_sel_hi:[0,1]
	v_pk_mul_f32 v[156:157], v[120:121], v[120:121]
	v_pk_mul_f32 v[128:129], v[118:119], v[118:119]
	v_add_f32_e32 v71, v156, v157
	v_add_f32_e32 v71, v128, v71
	v_pk_mul_f32 v[126:127], v[36:37], v[36:37]
	v_add_f32_e32 v71, v129, v71
	v_pk_mul_f32 v[116:117], v[86:87], v[116:117] op_sel_hi:[0,1]
	v_add_f32_e32 v71, v126, v71
	v_pk_mul_f32 v[124:125], v[116:117], v[116:117]
	v_lshlrev_b32_e32 v166, 16, v10
	v_and_b32_e32 v167, 0xffff0000, v10
	v_add_f32_e32 v71, v127, v71
	v_lshlrev_b32_e32 v162, 16, v11
	v_and_b32_e32 v163, 0xffff0000, v11
	v_pk_mul_f32 v[10:11], v[86:87], v[166:167] op_sel_hi:[0,1]
	v_add_f32_e32 v71, v124, v71
	v_pk_mul_f32 v[166:167], v[10:11], v[10:11]
	v_add_f32_e32 v71, v125, v71
	v_pk_mul_f32 v[162:163], v[86:87], v[162:163] op_sel_hi:[0,1]
	v_add_f32_e32 v71, v166, v71
	v_lshlrev_b32_e32 v160, 16, v12
	v_and_b32_e32 v161, 0xffff0000, v12
	v_pk_mul_f32 v[164:165], v[162:163], v[162:163]
	v_add_f32_e32 v71, v167, v71
	v_lshlrev_b32_e32 v122, 16, v13
	v_and_b32_e32 v123, 0xffff0000, v13
	v_pk_mul_f32 v[12:13], v[86:87], v[160:161] op_sel_hi:[0,1]
	v_add_f32_e32 v71, v164, v71
	v_pk_mul_f32 v[160:161], v[12:13], v[12:13]
	v_add_f32_e32 v71, v165, v71
	v_pk_mul_f32 v[122:123], v[86:87], v[122:123] op_sel_hi:[0,1]
	v_add_f32_e32 v71, v160, v71
	v_pk_mul_f32 v[158:159], v[122:123], v[122:123]
	v_lshlrev_b32_e32 v174, 16, v6
	v_and_b32_e32 v175, 0xffff0000, v6
	v_add_f32_e32 v71, v161, v71
	v_lshlrev_b32_e32 v170, 16, v7
	v_and_b32_e32 v171, 0xffff0000, v7
	v_pk_mul_f32 v[6:7], v[86:87], v[174:175] op_sel_hi:[0,1]
	v_add_f32_e32 v71, v158, v71
	v_pk_mul_f32 v[174:175], v[6:7], v[6:7]
	v_add_f32_e32 v71, v159, v71
	v_pk_mul_f32 v[170:171], v[86:87], v[170:171] op_sel_hi:[0,1]
	v_add_f32_e32 v71, v174, v71
	v_pk_mul_f32 v[172:173], v[170:171], v[170:171]
	v_add_f32_e32 v71, v175, v71
	v_add_f32_e32 v71, v172, v71
	v_pk_mul_f32 v[112:113], v[108:109], v[108:109]
	v_add_f32_e32 v71, v173, v71
	v_add_f32_e32 v71, v113, v71
	v_pk_mul_f32 v[114:115], v[8:9], v[8:9]
	v_add_f32_e32 v71, v112, v71
	v_add_f32_e32 v71, v115, v71
	v_add_f32_e32 v71, v114, v71
	ds_bpermute_b32 v73, v39, v71
	v_lshl_add_u64 v[34:35], v[110:111], 0, v[0:1]
	s_waitcnt lgkmcnt(0)
; DI unsigned pk2(float lo, float hi) { f32x2 v = {lo, hi}; bf16x2_t b = __builtin_convertvector(v, bf16x2_t); return __builtin_bit_cast(unsigned, b); }
; DI float bflo(unsigned w) { return __uint_as_float(w << 16); }
; DI float bfhi(unsigned w) { return __uint_as_float(w & 0xffff0000u); }
; DI void mla_finalize(PPtr p, int j, ldsp lds, int tid, int wave, int lane) {
;     ...
;                     const bf16_t* src = kvraw + (size_t)t * 2048 + head * 128;
; #pragma unroll
;                     for (int g = 0; g < 2; ++g) { const u32x4 w = *(const u32x4*)(src + 8 * (sub + 4 * g));
; #pragma unroll
;                         for (int i = 0; i < 4; ++i) { v[8 * g + 2 * i] = bflo(w[i]) * rkv; v[8 * g + 2 * i + 1] = bfhi(w[i]) * rkv; } }
;                     const u32x4 w = *(const u32x4*)(aout + (size_t)t * ADIMP + QL + KVL + 8 * sub);
; #pragma unroll
;                     for (int i = 0; i < 4; ++i) { v[16 + 2 * i] = bflo(w[i]); v[16 + 2 * i + 1] = bfhi(w[i]); }
;     ...
;                 for (int i = 0; i < 24; ++i) ss += v[i] * v[i];
;                 ss += __shfl_xor(ss, 1); ss += __shfl_xor(ss, 2);
;                 const float rs = rsqrtf(ss * (1.0f / QKH) + EPS);
;                 const float* gn = which == 0 ? qg : kg;
; #pragma unroll
;                 for (int g = 0; g < 3; ++g) { const f32x4 g0 = *(const f32x4*)(gn + 8 * (sub + 4 * g)), g1 = *(const f32x4*)(gn + 8 * (sub + 4 * g) + 4);
; #pragma unroll
;                     for (int i = 0; i < 4; ++i) { v[8 * g + i] *= rs * g0[i]; v[8 * g + 4 + i] *= rs * g1[i]; } }
; #pragma unroll
;                 for (int i = 0; i < 8; ++i) { const float mine = v[16 + i], other = __shfl_xor(mine, 2);
;                     v[16 + i] = (sub < 2) ? (mine * cj[i] - other * sj[i]) : (other * sj[i] + mine * cj[i]); }
;                 const float osc = which == 0 ? QSCALE : 1.0f;
;                 bf16_t* dst = (which == 0 ? Qb : Kb) + ((size_t)t * HEADS + head) * QKH;
; #pragma unroll
;                 for (int g = 0; g < 3; ++g) { u32x4 w;
; #pragma unroll
;                     for (int i = 0; i < 4; ++i) w[i] = pk2(v[8 * g + 2 * i] * osc, v[8 * g + 2 * i + 1] * osc);
;                     *(u32x4*)(dst + 8 * (sub + 4 * g)) = w; }
	v_add_f32_e32 v71, v71, v73
	ds_bpermute_b32 v73, v77, v71
	s_waitcnt lgkmcnt(0)
	v_add_f32_e32 v71, v71, v73
	v_fmamk_f32 v71, v71, 0x3c2aaaab, v152
	v_cmp_gt_f32_e64 s[8:9], s91, v71
	v_mul_f32_e32 v73, 0x4b800000, v71
	s_nop 0
	v_cndmask_b32_e64 v71, v71, v73, s[8:9]
	v_rsq_f32_e32 v71, v71
	s_nop 0
	v_mul_f32_e32 v73, 0x45800000, v71
	v_cndmask_b32_e64 v86, v71, v73, s[8:9]
	s_waitcnt vmcnt(3)
	v_pk_mul_f32 v[18:19], v[18:19], v[86:87] op_sel_hi:[1,0]
	v_pk_mul_f32 v[22:23], v[22:23], v[86:87] op_sel_hi:[1,0]
	v_pk_mul_f32 v[18:19], v[10:11], v[18:19]
	s_waitcnt vmcnt(2)
	v_pk_mul_f32 v[10:11], v[14:15], v[86:87] op_sel_hi:[1,0]
	v_pk_mul_f32 v[24:25], v[24:25], v[86:87] op_sel_hi:[1,0]
	v_pk_mul_f32 v[14:15], v[12:13], v[10:11]
	v_pk_mul_f32 v[10:11], v[20:21], v[86:87] op_sel_hi:[1,0]
	v_pk_mul_f32 v[22:23], v[120:121], v[22:23]
	v_pk_mul_f32 v[20:21], v[162:163], v[10:11]
	v_pk_mul_f32 v[10:11], v[16:17], v[86:87] op_sel_hi:[1,0]
	v_pk_mul_f32 v[26:27], v[26:27], v[86:87] op_sel_hi:[1,0]
	v_pk_mul_f32 v[16:17], v[122:123], v[10:11]
	s_waitcnt vmcnt(0)
	v_pk_mul_f32 v[10:11], v[30:31], v[86:87] op_sel_hi:[1,0]
	v_pk_mul_f32 v[24:25], v[118:119], v[24:25]
	v_pk_mul_f32 v[6:7], v[6:7], v[10:11]
	v_pk_mul_f32 v[10:11], v[32:33], v[86:87] op_sel_hi:[1,0]
	ds_bpermute_b32 v104, v77, v6
	ds_bpermute_b32 v103, v77, v7
	v_pk_mul_f32 v[10:11], v[170:171], v[10:11]
	ds_bpermute_b32 v98, v77, v10
	ds_bpermute_b32 v97, v77, v11
	v_pk_mul_f32 v[28:29], v[28:29], v[86:87] op_sel_hi:[1,0]
	s_waitcnt lgkmcnt(2)
	v_pk_mul_f32 v[12:13], v[104:105], v[102:103]
	v_pk_mul_f32 v[26:27], v[36:37], v[26:27]
	v_cndmask_b32_e64 v13, v13, -v13, s[6:7]
	v_cndmask_b32_e64 v12, v12, -v12, s[6:7]
	v_pk_fma_f32 v[6:7], v[6:7], v[100:101], v[12:13]
	s_waitcnt lgkmcnt(0)
	v_pk_mul_f32 v[12:13], v[98:99], v[96:97]
	v_pk_mul_f32 v[28:29], v[116:117], v[28:29]
	v_cndmask_b32_e64 v13, v13, -v13, s[6:7]
	v_cndmask_b32_e64 v12, v12, -v12, s[6:7]
	v_pk_fma_f32 v[30:31], v[10:11], v[94:95], v[12:13]
	v_pk_mul_f32 v[10:11], v[22:23], s[86:87] op_sel_hi:[1,0]
	v_pk_mul_f32 v[12:13], v[24:25], s[86:87] op_sel_hi:[1,0]
	v_pk_mul_f32 v[2:3], v[2:3], v[86:87] op_sel_hi:[1,0]
	v_cvt_pk_bf16_f32 v10, v10, v11
	v_cvt_pk_bf16_f32 v11, v12, v13
	v_pk_mul_f32 v[12:13], v[26:27], s[86:87] op_sel_hi:[1,0]
	v_pk_mul_f32 v[22:23], v[28:29], s[86:87] op_sel_hi:[1,0]
	v_pk_mul_f32 v[2:3], v[108:109], v[2:3] op_sel:[1,0] op_sel_hi:[0,1]
	v_cvt_pk_bf16_f32 v12, v12, v13
	v_cvt_pk_bf16_f32 v13, v22, v23
	ds_bpermute_b32 v92, v77, v2
	ds_bpermute_b32 v91, v77, v3
	global_store_dwordx4 v[34:35], v[10:13], off
	v_pk_mul_f32 v[6:7], v[6:7], s[86:87] op_sel_hi:[1,0]
	v_mov_b32_e32 v71, v1
	v_pk_mul_f32 v[10:11], v[18:19], s[86:87] op_sel_hi:[1,0]
	v_pk_mul_f32 v[12:13], v[20:21], s[86:87] op_sel_hi:[1,0]
	v_cvt_pk_bf16_f32 v10, v10, v11
	v_cvt_pk_bf16_f32 v11, v12, v13
	v_pk_mul_f32 v[12:13], v[14:15], s[86:87] op_sel_hi:[1,0]
	v_pk_mul_f32 v[14:15], v[16:17], s[86:87] op_sel_hi:[1,0]
	v_cvt_pk_bf16_f32 v12, v12, v13
	v_cvt_pk_bf16_f32 v13, v14, v15
	global_store_dwordx4 v[168:169], v[10:13], off
	v_mov_b32_e32 v103, v105
	v_mov_b32_e32 v97, v99
	v_cvt_pk_bf16_f32 v10, v6, v7
	v_pk_mul_f32 v[6:7], v[30:31], s[86:87] op_sel_hi:[1,0]
	s_nop 0
	v_cvt_pk_bf16_f32 v11, v6, v7
	s_waitcnt lgkmcnt(0)
	v_pk_mul_f32 v[6:7], v[92:93], v[90:91]
	v_mov_b32_e32 v91, v93
	v_cndmask_b32_e64 v7, v7, -v7, s[6:7]
	v_cndmask_b32_e64 v6, v6, -v6, s[6:7]
	v_pk_fma_f32 v[2:3], v[2:3], v[88:89], v[6:7]
	s_nop 0
	v_pk_mul_f32 v[2:3], v[2:3], s[86:87] op_sel_hi:[1,0]
	s_nop 0
	v_cvt_pk_bf16_f32 v12, v2, v3
	v_pk_mul_f32 v[2:3], v[4:5], v[86:87] op_sel_hi:[1,0]
	s_nop 0
	v_pk_mul_f32 v[2:3], v[8:9], v[2:3] op_sel:[1,0] op_sel_hi:[0,1]
	ds_bpermute_b32 v86, v77, v2
	ds_bpermute_b32 v83, v77, v3
	s_waitcnt lgkmcnt(0)
	v_pk_mul_f32 v[4:5], v[86:87], v[82:83]
	s_nop 0
	v_cndmask_b32_e64 v5, v5, -v5, s[6:7]
	v_cndmask_b32_e64 v4, v4, -v4, s[6:7]
	v_pk_fma_f32 v[2:3], v[2:3], v[80:81], v[4:5]
	v_mov_b32_e32 v83, v87
	v_pk_mul_f32 v[2:3], v[2:3], s[86:87] op_sel_hi:[1,0]
	v_mov_b32_e32 v6, v188
	v_mov_b32_e32 v7, v189
	v_mov_b32_e32 v8, v190
	v_mov_b32_e32 v9, v191
	v_lshlrev_b32_e32 v166, 16, v6
	v_cvt_pk_bf16_f32 v13, v2, v3
	v_lshl_add_u64 v[2:3], v[110:111], 0, v[70:71]
	global_store_dwordx4 v[2:3], v[10:13], off
	v_and_b32_e32 v167, 0xffff0000, v6
	v_lshlrev_b32_e32 v162, 16, v7
	v_lshl_add_u64 v[10:11], v[78:79], 0, v[0:1]
	v_and_b32_e32 v163, 0xffff0000, v7
	v_pk_mul_f32 v[6:7], v[166:167], v[166:167]
	v_pk_mul_f32 v[164:165], v[162:163], v[162:163]
	v_and_b32_e32 v10, 0xffff0000, v8
	v_lshlrev_b32_e32 v11, 16, v8
	v_pk_mul_f32 v[32:33], v[10:11], v[10:11]
	v_and_b32_e32 v8, 0xffff0000, v9
	v_lshlrev_b32_e32 v9, 16, v9
	v_pk_mul_f32 v[34:35], v[8:9], v[8:9]
	v_mov_b32_e32 v2, v210
	v_mov_b32_e32 v3, v211
	v_mov_b32_e32 v4, v212
	v_mov_b32_e32 v5, v213
	v_lshlrev_b32_e32 v24, 16, v5
	v_and_b32_e32 v25, 0xffff0000, v5
	v_pk_mul_f32 v[36:37], v[76:77], v[24:25] op_sel_hi:[0,1]
	v_lshlrev_b32_e32 v24, 16, v4
	v_and_b32_e32 v25, 0xffff0000, v4
	v_lshlrev_b32_e32 v4, 16, v3
	v_and_b32_e32 v5, 0xffff0000, v3
	v_pk_mul_f32 v[112:113], v[76:77], v[4:5] op_sel_hi:[0,1]
	v_lshlrev_b32_e32 v4, 16, v2
	v_and_b32_e32 v5, 0xffff0000, v2
	v_mov_b32_e32 v12, v218
	v_mov_b32_e32 v13, v219
	v_mov_b32_e32 v14, v220
	v_mov_b32_e32 v15, v221
	v_lshlrev_b32_e32 v2, 16, v15
	v_and_b32_e32 v3, 0xffff0000, v15
	v_pk_mul_f32 v[120:121], v[76:77], v[2:3] op_sel_hi:[0,1]
	v_lshlrev_b32_e32 v2, 16, v14
	v_and_b32_e32 v3, 0xffff0000, v14
	v_pk_mul_f32 v[124:125], v[76:77], v[2:3] op_sel_hi:[0,1]
	v_lshlrev_b32_e32 v2, 16, v13
	v_and_b32_e32 v3, 0xffff0000, v13
; DI float bflo(unsigned w) { return __uint_as_float(w << 16); }
; DI float bfhi(unsigned w) { return __uint_as_float(w & 0xffff0000u); }
; DI void mla_finalize(PPtr p, int j, ldsp lds, int tid, int wave, int lane) {
;     ...
;                     const bf16_t* src = kvraw + (size_t)t * 2048 + head * 128;
; #pragma unroll
;                     for (int g = 0; g < 2; ++g) { const u32x4 w = *(const u32x4*)(src + 8 * (sub + 4 * g));
; #pragma unroll
;                         for (int i = 0; i < 4; ++i) { v[8 * g + 2 * i] = bflo(w[i]) * rkv; v[8 * g + 2 * i + 1] = bfhi(w[i]) * rkv; } }
;                     const u32x4 w = *(const u32x4*)(aout + (size_t)t * ADIMP + QL + KVL + 8 * sub);
; #pragma unroll
;                     for (int i = 0; i < 4; ++i) { v[16 + 2 * i] = bflo(w[i]); v[16 + 2 * i + 1] = bfhi(w[i]); }
;                 }
;                 float ss = 0.f;
; #pragma unroll
;                 for (int i = 0; i < 24; ++i) ss += v[i] * v[i];
;                 ss += __shfl_xor(ss, 1); ss += __shfl_xor(ss, 2);
;                 const float rs = rsqrtf(ss * (1.0f / QKH) + EPS);
;                 const float* gn = which == 0 ? qg : kg;
; #pragma unroll
;                 for (int g = 0; g < 3; ++g) { const f32x4 g0 = *(const f32x4*)(gn + 8 * (sub + 4 * g)), g1 = *(const f32x4*)(gn + 8 * (sub + 4 * g) + 4);
; #pragma unroll
;                     for (int i = 0; i < 4; ++i) { v[8 * g + i] *= rs * g0[i]; v[8 * g + 4 + i] *= rs * g1[i]; } }
; #pragma unroll
;                 for (int i = 0; i < 8; ++i) { const float mine = v[16 + i], other = __shfl_xor(mine, 2);
;                     v[16 + i] = (sub < 2) ? (mine * cj[i] - other * sj[i]) : (other * sj[i] + mine * cj[i]); }
	v_pk_mul_f32 v[128:129], v[76:77], v[2:3] op_sel_hi:[0,1]
	v_lshlrev_b32_e32 v2, 16, v12
	v_and_b32_e32 v3, 0xffff0000, v12
	v_pk_mul_f32 v[108:109], v[76:77], v[24:25] op_sel_hi:[0,1]
	v_pk_mul_f32 v[116:117], v[76:77], v[4:5] op_sel_hi:[0,1]
	v_pk_mul_f32 v[158:159], v[76:77], v[2:3] op_sel_hi:[0,1]
	v_pk_mul_f32 v[118:119], v[116:117], v[116:117]
	v_pk_mul_f32 v[114:115], v[112:113], v[112:113]
	v_add_f32_e32 v73, v118, v119
	v_add_f32_e32 v73, v114, v73
	v_pk_mul_f32 v[110:111], v[108:109], v[108:109]
	v_add_f32_e32 v73, v115, v73
	v_add_f32_e32 v73, v110, v73
	v_pk_mul_f32 v[106:107], v[36:37], v[36:37]
	v_add_f32_e32 v73, v111, v73
	v_add_f32_e32 v73, v106, v73
	v_pk_mul_f32 v[160:161], v[158:159], v[158:159]
	v_add_f32_e32 v73, v107, v73
	v_add_f32_e32 v73, v160, v73
	v_pk_mul_f32 v[156:157], v[128:129], v[128:129]
	v_add_f32_e32 v73, v161, v73
	v_add_f32_e32 v73, v156, v73
	v_pk_mul_f32 v[126:127], v[124:125], v[124:125]
	v_add_f32_e32 v73, v157, v73
	v_add_f32_e32 v73, v126, v73
	v_pk_mul_f32 v[122:123], v[120:121], v[120:121]
	v_add_f32_e32 v73, v127, v73
	v_add_f32_e32 v73, v122, v73
	v_add_f32_e32 v73, v123, v73
	v_add_f32_e32 v6, v6, v73
	v_add_f32_e32 v6, v7, v6
	v_add_f32_e32 v6, v164, v6
	v_add_f32_e32 v6, v165, v6
	v_add_f32_e32 v6, v33, v6
	v_add_f32_e32 v6, v32, v6
	v_add_f32_e32 v6, v35, v6
	v_add_f32_e32 v6, v34, v6
	ds_bpermute_b32 v7, v39, v6
	v_mov_b32_e32 v73, v1
	s_waitcnt lgkmcnt(0)
	v_add_f32_e32 v6, v6, v7
	ds_bpermute_b32 v7, v77, v6
	s_waitcnt lgkmcnt(0)
	v_add_f32_e32 v6, v6, v7
	v_fmamk_f32 v6, v6, 0x3c2aaaab, v152
	v_cmp_gt_f32_e64 s[8:9], s91, v6
	v_mul_f32_e32 v7, 0x4b800000, v6
	s_nop 0
	v_cndmask_b32_e64 v6, v6, v7, s[8:9]
	v_rsq_f32_e32 v6, v6
	s_nop 0
	v_mul_f32_e32 v7, 0x45800000, v6
	v_cndmask_b32_e64 v6, v6, v7, s[8:9]
	v_mov_b32_e32 v16, v230
	v_mov_b32_e32 v17, v231
	v_mov_b32_e32 v18, v232
	v_mov_b32_e32 v19, v233
	v_mov_b32_e32 v20, v234
	v_mov_b32_e32 v21, v235
	v_mov_b32_e32 v22, v236
	v_mov_b32_e32 v23, v237
	v_pk_mul_f32 v[20:21], v[20:21], v[6:7] op_sel_hi:[1,0]
	v_pk_mul_f32 v[16:17], v[16:17], v[6:7] op_sel_hi:[1,0]
	v_pk_mul_f32 v[22:23], v[22:23], v[6:7] op_sel_hi:[1,0]
	v_pk_mul_f32 v[18:19], v[18:19], v[6:7] op_sel_hi:[1,0]
	s_mov_b64 s[8:9], 0x18a40000
	v_pk_mul_f32 v[20:21], v[116:117], v[20:21]
	v_pk_mul_f32 v[16:17], v[108:109], v[16:17]
	v_pk_mul_f32 v[22:23], v[112:113], v[22:23]
	v_pk_mul_f32 v[18:19], v[36:37], v[18:19]
	v_mov_b32_e32 v24, v238
	v_mov_b32_e32 v25, v239
	v_mov_b32_e32 v26, v240
	v_mov_b32_e32 v27, v241
	v_pk_mul_f32 v[24:25], v[24:25], v[6:7] op_sel_hi:[1,0]
	v_mov_b32_e32 v28, v242
	v_mov_b32_e32 v29, v243
	v_mov_b32_e32 v30, v244
	v_mov_b32_e32 v31, v245
	v_pk_mul_f32 v[28:29], v[28:29], v[6:7] op_sel_hi:[1,0]
	v_mov_b32_e32 v2, v246
	v_mov_b32_e32 v3, v247
	v_mov_b32_e32 v4, v248
	v_mov_b32_e32 v5, v249
	v_pk_mul_f32 v[2:3], v[2:3], v[6:7] op_sel_hi:[1,0]
	v_mov_b32_e32 v12, v250
	v_mov_b32_e32 v13, v251
	v_mov_b32_e32 v14, v252
	v_mov_b32_e32 v15, v253
	v_pk_mul_f32 v[12:13], v[12:13], v[6:7] op_sel_hi:[1,0]
	v_pk_mul_f32 v[2:3], v[2:3], v[10:11] op_sel:[0,1] op_sel_hi:[1,0]
	ds_bpermute_b32 v10, v77, v2
	ds_bpermute_b32 v11, v77, v3
	v_pk_mul_f32 v[12:13], v[12:13], v[166:167]
	ds_bpermute_b32 v32, v77, v12
	ds_bpermute_b32 v33, v77, v13
	v_pk_mul_f32 v[14:15], v[14:15], v[6:7] op_sel_hi:[1,0]
	s_waitcnt lgkmcnt(2)
	v_pk_mul_f32 v[10:11], v[90:91], v[10:11]
	v_pk_mul_f32 v[14:15], v[14:15], v[162:163]
	v_cndmask_b32_e64 v11, v11, -v11, s[6:7]
	v_cndmask_b32_e64 v10, v10, -v10, s[6:7]
	v_pk_fma_f32 v[10:11], v[2:3], v[88:89], v[10:11]
	v_pk_mul_f32 v[2:3], v[4:5], v[6:7] op_sel_hi:[1,0]
	s_waitcnt lgkmcnt(0)
	v_pk_mul_f32 v[32:33], v[102:103], v[32:33]
	v_pk_mul_f32 v[2:3], v[2:3], v[8:9] op_sel:[0,1] op_sel_hi:[1,0]
	v_cndmask_b32_e64 v33, v33, -v33, s[6:7]
	v_cndmask_b32_e64 v32, v32, -v32, s[6:7]
	ds_bpermute_b32 v4, v77, v2
	ds_bpermute_b32 v5, v77, v3
	v_pk_fma_f32 v[12:13], v[12:13], v[100:101], v[32:33]
	ds_bpermute_b32 v32, v77, v14
	ds_bpermute_b32 v33, v77, v15
	v_pk_mul_f32 v[30:31], v[30:31], v[6:7] op_sel_hi:[1,0]
	s_waitcnt lgkmcnt(2)
	v_pk_mul_f32 v[4:5], v[82:83], v[4:5]
	v_pk_mul_f32 v[26:27], v[26:27], v[6:7] op_sel_hi:[1,0]
	v_cndmask_b32_e64 v5, v5, -v5, s[6:7]
	s_waitcnt lgkmcnt(0)
; DI void mla_finalize(PPtr p, int j, ldsp lds, int tid, int wave, int lane) {
;     ...
;             const int tok = wave * 4 + rr, t = t0 + tok;
;             float ssq = 0.f, sskv = 0.f;
;             if (lane < 48) { const u32x4 w = *(const u32x4*)(aout + (size_t)t * ADIMP + 8 * lane);
; #pragma unroll
;                 for (int i = 0; i < 4; ++i) { const float a = bflo(w[i]), c = bfhi(w[i]); ssq += a * a + c * c; } }
;             if (lane < 32) { const u32x4 w = *(const u32x4*)(aout + (size_t)t * ADIMP + QL + 8 * lane);
; #pragma unroll
;                 for (int i = 0; i < 4; ++i) { const float a = bflo(w[i]), c = bfhi(w[i]); sskv += a * a + c * c; } }
;             const float rq = rsqrtf(wave_sum(ssq) * (1.0f / QL) + EPS), rkv = rsqrtf(wave_sum(sskv) * (1.0f / KVL) + EPS);
;             float cs, sn;
;             { const int fi = lane & 15; const float inv = exp2f(-(float)fi * (13.287712379549449f / 16.0f));
;               const float ang = (float)p->pos[t] * inv; double rev = (double)ang * 0.15915494309189535; rev -= floor(rev); const float rv = (float)rev;
;               cs = __builtin_amdgcn_cosf(rv); sn = __builtin_amdgcn_sinf(rv); }
;     ...
; #pragma unroll
;                 for (int i = 0; i < 8; ++i) { const float mine = v[16 + i], other = __shfl_xor(mine, 2);
;                     v[16 + i] = (sub < 2) ? (mine * cj[i] - other * sj[i]) : (other * sj[i] + mine * cj[i]); }
;                 const float osc = which == 0 ? QSCALE : 1.0f;
;                 bf16_t* dst = (which == 0 ? Qb : Kb) + ((size_t)t * HEADS + head) * QKH;
; #pragma unroll
;                 for (int g = 0; g < 3; ++g) { u32x4 w;
; #pragma unroll
;                     for (int i = 0; i < 4; ++i) w[i] = pk2(v[8 * g + 2 * i] * osc, v[8 * g + 2 * i + 1] * osc);
;                     *(u32x4*)(dst + 8 * (sub + 4 * g)) = w; }
;             }
;             { const bf16_t* src = kvraw + (size_t)t * 2048 + head * 128 + 64 + 16 * sub;
; #pragma unroll
;               for (int g = 0; g < 2; ++g) { const u32x4 w = *(const u32x4*)(src + 8 * g);
; #pragma unroll
;                   for (int i = 0; i < 4; ++i) { const int d = head * 64 + 16 * sub + 8 * g + 2 * i;
;                       *(LAS bf16_t*)(lds + ((d) * VTP + tok) * 2) = f2bf(bflo(w[i]) * rkv);
;                       *(LAS bf16_t*)(lds + ((d + 1) * VTP + tok) * 2) = f2bf(bfhi(w[i]) * rkv); } } }
	v_pk_mul_f32 v[32:33], v[96:97], v[32:33]
	v_cndmask_b32_e64 v4, v4, -v4, s[6:7]
	v_lshl_add_u64 v[8:9], v[84:85], 0, s[8:9]
	v_pk_mul_f32 v[28:29], v[158:159], v[28:29]
	v_pk_mul_f32 v[24:25], v[124:125], v[24:25]
	v_pk_mul_f32 v[30:31], v[128:129], v[30:31]
	v_pk_mul_f32 v[26:27], v[120:121], v[26:27]
	v_cndmask_b32_e64 v33, v33, -v33, s[6:7]
	v_cndmask_b32_e64 v32, v32, -v32, s[6:7]
	v_pk_fma_f32 v[6:7], v[2:3], v[80:81], v[4:5]
	v_cvt_pk_bf16_f32 v2, v20, v21
	v_cvt_pk_bf16_f32 v3, v22, v23
	v_cvt_pk_bf16_f32 v4, v16, v17
	v_cvt_pk_bf16_f32 v5, v18, v19
	v_lshl_add_u64 v[16:17], v[8:9], 0, v[0:1]
	v_pk_fma_f32 v[14:15], v[14:15], v[94:95], v[32:33]
	global_store_dwordx4 v[16:17], v[2:5], off
	v_lshl_add_u64 v[16:17], v[8:9], 0, v[68:69]
	s_nop 0
	v_cvt_pk_bf16_f32 v2, v28, v29
	v_cvt_pk_bf16_f32 v3, v30, v31
	v_cvt_pk_bf16_f32 v4, v24, v25
	v_cvt_pk_bf16_f32 v5, v26, v27
	global_store_dwordx4 v[16:17], v[2:5], off
	s_nop 1
	v_cvt_pk_bf16_f32 v2, v12, v13
	v_cvt_pk_bf16_f32 v3, v14, v15
	v_cvt_pk_bf16_f32 v4, v10, v11
	v_cvt_pk_bf16_f32 v5, v6, v7
	v_lshl_add_u64 v[6:7], v[8:9], 0, v[70:71]
	global_store_dwordx4 v[6:7], v[2:5], off
	v_lshl_add_u64 v[6:7], v[78:79], 0, v[72:73]
	s_nop 0
	v_add_u32_e32 v11, s20, v143
	v_add_u32_e32 v176, 0xa000, v11
	s_add_i32 s20, s20, 2
	s_cmp_eq_u32 s20, 8
	v_mov_b32_e32 v2, v222
	v_mov_b32_e32 v3, v223
	v_mov_b32_e32 v4, v224
	v_mov_b32_e32 v5, v225
	v_mov_b32_e32 v6, v226
	v_mov_b32_e32 v7, v227
	v_mov_b32_e32 v8, v228
	v_mov_b32_e32 v9, v229
	v_lshlrev_b32_e32 v10, 16, v6
	v_and_b32_e32 v6, 0xffff0000, v6
	v_mul_f32_e32 v6, v76, v6
	v_cvt_pk_bf16_f32 v6, v6, s0
	ds_write_b16 v11, v6 offset:5120
	v_lshlrev_b32_e32 v6, 16, v7
	v_mul_f32_e32 v6, v76, v6
	v_cvt_pk_bf16_f32 v6, v6, s0
	ds_write_b16 v11, v6 offset:10240
	v_and_b32_e32 v6, 0xffff0000, v7
	v_mul_f32_e32 v6, v76, v6
	v_cvt_pk_bf16_f32 v6, v6, s0
	ds_write_b16 v11, v6 offset:15360
	v_lshlrev_b32_e32 v6, 16, v8
	v_mul_f32_e32 v6, v76, v6
	v_cvt_pk_bf16_f32 v6, v6, s0
	ds_write_b16 v11, v6 offset:20480
	v_and_b32_e32 v6, 0xffff0000, v8
	v_mul_f32_e32 v6, v76, v6
	v_cvt_pk_bf16_f32 v6, v6, s0
	ds_write_b16 v11, v6 offset:25600
	v_lshlrev_b32_e32 v6, 16, v9
	v_mul_f32_e32 v6, v76, v6
	v_cvt_pk_bf16_f32 v6, v6, s0
	ds_write_b16 v11, v6 offset:30720
	v_and_b32_e32 v6, 0xffff0000, v9
	v_mul_f32_e32 v6, v76, v6
	v_cvt_pk_bf16_f32 v6, v6, s0
	ds_write_b16 v11, v6 offset:35840
	v_lshlrev_b32_e32 v6, 16, v2
	v_and_b32_e32 v2, 0xffff0000, v2
	v_mul_f32_e32 v2, v76, v2
	v_cvt_pk_bf16_f32 v2, v2, s0
	ds_write_b16 v176, v2 offset:5120
	v_lshlrev_b32_e32 v2, 16, v3
	v_mul_f32_e32 v2, v76, v2
	v_cvt_pk_bf16_f32 v2, v2, s0
	ds_write_b16 v176, v2 offset:10240
	v_and_b32_e32 v2, 0xffff0000, v3
	v_mul_f32_e32 v2, v76, v2
	v_cvt_pk_bf16_f32 v2, v2, s0
	ds_write_b16 v176, v2 offset:15360
	v_lshlrev_b32_e32 v2, 16, v4
	v_mul_f32_e32 v2, v76, v2
	v_cvt_pk_bf16_f32 v2, v2, s0
	ds_write_b16 v176, v2 offset:20480
	v_and_b32_e32 v2, 0xffff0000, v4
	v_mul_f32_e32 v2, v76, v2
	v_cvt_pk_bf16_f32 v2, v2, s0
	ds_write_b16 v176, v2 offset:25600
	v_lshlrev_b32_e32 v2, 16, v5
	v_mul_f32_e32 v2, v76, v2
	v_cvt_pk_bf16_f32 v2, v2, s0
	ds_write_b16 v176, v2 offset:30720
	v_and_b32_e32 v2, 0xffff0000, v5
	v_mul_f32_e32 v10, v76, v10
	v_mul_f32_e32 v6, v76, v6
	v_mul_f32_e32 v2, v76, v2
	v_cvt_pk_bf16_f32 v10, v10, s0
	v_cvt_pk_bf16_f32 v6, v6, s0
	v_cvt_pk_bf16_f32 v2, v2, s0
	ds_write_b16 v11, v10
	ds_write_b16 v176, v6
	ds_write_b16 v176, v2 offset:35840
	s_cbranch_scc1 .LBB0_784
.LBB0_787:
	s_mul_hi_i32 s9, s14, 0x600
	s_mul_i32 s8, s14, 0x600
	v_mov_b32_e32 v3, 0
	v_lshl_add_u64 v[4:5], v[42:43], 0, s[8:9]
	v_mov_b32_e32 v2, 0
	global_load_dwordx4 v[180:183], v[4:5], off
	global_load_dwordx4 v[184:187], v[4:5], off offset:768
	v_lshl_add_u64 v[176:177], v[64:65], 0, s[8:9]
	s_mul_i32 s28, s14, 0xc00
	s_mov_b32 s29, 0
	global_load_dwordx4 v[188:191], v[176:177], off offset:1280
	v_lshl_add_u64 v[176:177], v[66:67], 0, s[28:29]
	s_lshl_b32 s28, s14, 12
	v_mov_b32_e32 v178, v72
	v_mov_b32_e32 v179, v1
	global_load_dwordx4 v[192:195], v[176:177], off
	global_load_dwordx4 v[196:199], v[176:177], off offset:64
	global_load_dwordx4 v[206:209], v[176:177], off offset:128
	v_lshl_add_u64 v[176:177], v[40:41], 0, s[28:29]
	v_lshl_add_u64 v[178:179], v[176:177], 0, v[178:179]
	v_lshl_add_u64 v[176:177], v[176:177], 0, v[0:1]
	global_load_dwordx4 v[222:225], v[178:179], off offset:144
	global_load_dwordx4 v[226:229], v[178:179], off offset:128
	global_load_dwordx4 v[210:213], v[176:177], off
	global_load_dwordx4 v[218:221], v[176:177], off offset:64
	s_lshl_b32 s26, s14, 2
	s_add_u32 s26, s12, s26
	s_addc_u32 s27, s13, 0
	global_load_dword v179, v1, s[26:27]
	s_waitcnt vmcnt(0)
	s_and_saveexec_b64 s[10:11], vcc
	s_cbranch_execz .LBB0_789
	v_mov_b32_e32 v6, v180
	v_mov_b32_e32 v7, v181
	v_mov_b32_e32 v8, v182
	v_mov_b32_e32 v9, v183
	v_lshlrev_b32_e32 v11, 16, v7
	v_lshlrev_b32_e32 v10, 16, v6
	v_and_b32_e32 v7, 0xffff0000, v7
	v_and_b32_e32 v6, 0xffff0000, v6
	v_pk_mul_f32 v[6:7], v[6:7], v[6:7]
	s_nop 0
	v_pk_fma_f32 v[6:7], v[10:11], v[10:11], v[6:7]
	v_lshlrev_b32_e32 v11, 16, v9
	v_lshlrev_b32_e32 v10, 16, v8
	v_and_b32_e32 v9, 0xffff0000, v9
	v_and_b32_e32 v8, 0xffff0000, v8
	v_pk_mul_f32 v[8:9], v[8:9], v[8:9]
	v_add_f32_e32 v2, v6, v7
	v_pk_fma_f32 v[8:9], v[10:11], v[10:11], v[8:9]
	s_nop 0
	v_add_f32_e32 v2, v8, v2
	v_add_f32_e32 v2, v9, v2
